# attention phases: remaining plain v_pk_add_f32 in peeled and sample-unit tile loops split into v_add_f32
# baseline (speedup 1.0000x reference)
.LBB0_595:
	v_exp_f32_e32 v16, v0
	v_exp_f32_e32 v18, v1
	v_exp_f32_e32 v20, v2
	v_exp_f32_e32 v22, v3
	v_exp_f32_e32 v24, v4
	v_exp_f32_e32 v26, v5
	v_exp_f32_e32 v28, v6
	v_exp_f32_e32 v30, v7
	v_cvt_pk_bf16_f32 v0, v16, v18
	v_cvt_pk_bf16_f32 v1, v20, v22
	v_cvt_pk_bf16_f32 v2, v24, v26
	v_cvt_pk_bf16_f32 v3, v28, v30
	v_exp_f32_e32 v8, v8
	v_exp_f32_e32 v66, v9
	s_waitcnt lgkmcnt(0)
	v_mfma_f32_32x32x16_bf16 v[96:111], v[60:63], v[0:3], v[96:111]
	v_exp_f32_e32 v10, v10
	v_exp_f32_e32 v68, v11
	v_exp_f32_e32 v12, v12
	v_exp_f32_e32 v60, v13
	v_exp_f32_e32 v14, v14
	v_exp_f32_e32 v62, v15
	v_exp_f32_e32 v17, v112
	v_mfma_f32_32x32x16_bf16 v[80:95], v[56:59], v[0:3], v[80:95]
	v_cvt_pk_bf16_f32 v0, v8, v66
	v_cvt_pk_bf16_f32 v1, v10, v68
	v_cvt_pk_bf16_f32 v2, v12, v60
	v_cvt_pk_bf16_f32 v3, v14, v62
	v_exp_f32_e32 v19, v113
	v_exp_f32_e32 v21, v114
	v_exp_f32_e32 v23, v115
	v_mfma_f32_32x32x16_bf16 v[96:111], v[52:55], v[0:3], v[96:111]
	v_exp_f32_e32 v25, v116
	v_exp_f32_e32 v27, v117
	v_exp_f32_e32 v29, v118
	v_exp_f32_e32 v31, v119
	v_add_f32_e64 v4, v16, 0
	v_add_f32_e64 v5, v17, 0
	v_exp_f32_e32 v9, v120
	v_add_f32_e32 v4, v18, v4
	v_add_f32_e32 v5, v19, v5
	v_mfma_f32_32x32x16_bf16 v[80:95], v[48:51], v[0:3], v[80:95]
	v_cvt_pk_bf16_f32 v0, v17, v19
	v_cvt_pk_bf16_f32 v1, v21, v23
	v_cvt_pk_bf16_f32 v2, v25, v27
	v_cvt_pk_bf16_f32 v3, v29, v31
	v_add_f32_e64 v4, v20, v4
	v_add_f32_e64 v5, v21, v5
	v_exp_f32_e32 v67, v121
	v_add_f32_e32 v16, v22, v4
	v_add_f32_e32 v17, v23, v5
	v_mfma_f32_32x32x16_bf16 v[96:111], v[44:47], v[0:3], v[96:111]
	v_exp_f32_e32 v11, v122
	v_exp_f32_e32 v69, v123
	v_exp_f32_e32 v13, v124
	v_exp_f32_e32 v61, v125
	v_exp_f32_e32 v15, v126
	v_exp_f32_e32 v63, v127
	v_cvt_pk_bf16_f32 v4, v9, v67
	v_mfma_f32_32x32x16_bf16 v[80:95], v[40:43], v[0:3], v[80:95]
	v_add_f32_e64 v0, v24, v16
	v_add_f32_e64 v1, v25, v17
	v_cvt_pk_bf16_f32 v5, v11, v69
	v_add_f32_e64 v0, v26, v0
	v_add_f32_e64 v1, v27, v1
	v_cvt_pk_bf16_f32 v6, v13, v61
	v_add_f32_e32 v0, v28, v0
	v_add_f32_e32 v1, v29, v1
	v_cvt_pk_bf16_f32 v7, v15, v63
	v_add_f32_e32 v0, v30, v0
	v_add_f32_e32 v1, v31, v1
	s_nop 0
	v_add_f32_e32 v0, v8, v0
	v_add_f32_e32 v1, v9, v1
	v_mfma_f32_32x32x16_bf16 v[96:111], v[36:39], v[4:7], v[96:111]
	v_add_f32_e64 v0, v66, v0
	v_add_f32_e64 v1, v67, v1
	v_add_f32_e64 v0, v10, v0
	v_add_f32_e64 v1, v11, v1
	v_add_f32_e64 v0, v68, v0
	v_add_f32_e64 v1, v69, v1
	v_add_f32_e32 v0, v12, v0
	v_add_f32_e32 v1, v13, v1
	v_mfma_f32_32x32x16_bf16 v[80:95], v[32:35], v[4:7], v[80:95]
	v_add_f32_e64 v0, v60, v0
	v_add_f32_e64 v1, v61, v1
	v_add_f32_e64 v0, v14, v0
	v_add_f32_e64 v1, v15, v1
	v_add_f32_e64 v0, v62, v0
	v_add_f32_e64 v1, v63, v1
	v_add_f32_e32 v0, v0, v1
	v_add_f32_e32 v171, v171, v0

.LBB0_632:
	v_exp_f32_e32 v0, v48
	v_exp_f32_e32 v48, v49
	v_exp_f32_e32 v2, v50
	v_exp_f32_e32 v160, v51
	v_exp_f32_e32 v4, v52
	v_exp_f32_e32 v162, v53
	v_exp_f32_e32 v6, v54
	v_exp_f32_e32 v54, v55
	v_cvt_pk_bf16_f32 v50, v0, v48
	v_cvt_pk_bf16_f32 v51, v2, v160
	v_cvt_pk_bf16_f32 v52, v4, v162
	v_cvt_pk_bf16_f32 v53, v6, v54
	v_exp_f32_e32 v8, v56
	v_exp_f32_e32 v56, v57
	v_mfma_f32_32x32x16_bf16 v[112:127], v[12:15], v[50:53], v[112:127]
	v_exp_f32_e32 v10, v58
	v_exp_f32_e32 v58, v59
	v_exp_f32_e32 v12, v60
	v_exp_f32_e32 v60, v61
	v_exp_f32_e32 v14, v62
	v_exp_f32_e32 v62, v63
	v_exp_f32_e32 v1, v32
	v_mfma_f32_32x32x16_bf16 v[80:95], v[156:159], v[50:53], v[80:95]
	v_exp_f32_e32 v49, v33
	v_exp_f32_e32 v3, v34
	v_exp_f32_e32 v161, v35
	v_cvt_pk_bf16_f32 v32, v8, v56
	v_cvt_pk_bf16_f32 v33, v10, v58
	v_cvt_pk_bf16_f32 v34, v12, v60
	v_cvt_pk_bf16_f32 v35, v14, v62
	v_exp_f32_e32 v5, v36
	v_exp_f32_e32 v163, v37
	v_mfma_f32_32x32x16_bf16 v[112:127], v[152:155], v[32:35], v[112:127]
	v_exp_f32_e32 v7, v38
	v_exp_f32_e32 v55, v39
	v_exp_f32_e32 v9, v40
	v_exp_f32_e32 v57, v41
	v_exp_f32_e32 v11, v42
	v_exp_f32_e32 v59, v43
	v_exp_f32_e32 v13, v44
	v_mfma_f32_32x32x16_bf16 v[80:95], v[148:151], v[32:35], v[80:95]
	v_cvt_pk_bf16_f32 v32, v1, v49
	v_cvt_pk_bf16_f32 v33, v3, v161
	v_cvt_pk_bf16_f32 v34, v5, v163
	v_cvt_pk_bf16_f32 v35, v7, v55
	v_exp_f32_e32 v61, v45
	v_exp_f32_e32 v15, v46
	v_exp_f32_e32 v63, v47
	v_mfma_f32_32x32x16_bf16 v[112:127], v[28:31], v[32:35], v[112:127]
	v_add_f32_e64 v28, v0, 0
	v_add_f32_e64 v29, v1, 0
	v_cvt_pk_bf16_f32 v30, v13, v61
	v_add_f32_e64 v28, v48, v28
	v_add_f32_e64 v29, v49, v29
	v_cvt_pk_bf16_f32 v31, v15, v63
	v_add_f32_e32 v28, v2, v28
	v_add_f32_e32 v29, v3, v29
	v_mov_b32_e32 v38, v6
	v_add_f32_e32 v36, v160, v28
	v_add_f32_e32 v37, v161, v29
	v_mfma_f32_32x32x16_bf16 v[80:95], v[24:27], v[32:35], v[80:95]
	v_add_f32_e64 v24, v4, v36
	v_add_f32_e64 v25, v5, v37
	v_cvt_pk_bf16_f32 v28, v9, v57
	v_add_f32_e64 v24, v162, v24
	v_add_f32_e64 v25, v163, v25
	v_cvt_pk_bf16_f32 v29, v11, v59
	v_add_f32_e32 v24, v6, v24
	v_add_f32_e32 v25, v7, v25
	v_mov_b32_e32 v32, v0
	v_add_f32_e32 v24, v54, v24
	v_add_f32_e32 v25, v55, v25
	v_mfma_f32_32x32x16_bf16 v[112:127], v[20:23], v[28:31], v[112:127]
	v_add_f32_e64 v24, v8, v24
	v_add_f32_e64 v25, v9, v25
	v_mov_b32_e32 v33, v48
	v_add_f32_e64 v24, v56, v24
	v_add_f32_e64 v25, v57, v25
	v_mov_b32_e32 v34, v2
	v_add_f32_e32 v20, v10, v24
	v_add_f32_e32 v21, v11, v25
	v_mov_b32_e32 v35, v160
	v_add_f32_e32 v20, v58, v20
	v_add_f32_e32 v21, v59, v21
	v_mfma_f32_32x32x16_bf16 v[80:95], v[16:19], v[28:31], v[80:95]
	v_add_f32_e64 v20, v12, v20
	v_add_f32_e64 v21, v13, v21
	v_mov_b32_e32 v36, v4
	v_add_f32_e64 v20, v60, v20
	v_add_f32_e64 v21, v61, v21
	v_mov_b32_e32 v37, v162
	v_add_f32_e32 v20, v14, v20
	v_add_f32_e32 v21, v15, v21
	v_mov_b32_e32 v39, v54
	v_add_f32_e32 v20, v62, v20
	v_add_f32_e32 v21, v63, v21
	v_mov_b32_e32 v40, v8
	v_add_f32_e32 v20, v20, v21
	v_add_f32_e32 v202, v202, v20
	v_mov_b32_e32 v41, v56
	v_mov_b32_e32 v42, v10
	v_mov_b32_e32 v43, v58
	v_mov_b32_e32 v44, v12
	v_mov_b32_e32 v45, v60
	v_mov_b32_e32 v46, v14
	v_mov_b32_e32 v47, v62
	s_mov_b64 s[38:39], 0
	v_mov_b32_e32 v31, v63
	v_mov_b32_e32 v30, v15
	v_mov_b32_e32 v29, v61
	v_mov_b32_e32 v28, v13
	v_mov_b32_e32 v27, v59
	v_mov_b32_e32 v26, v11
	v_mov_b32_e32 v25, v57
	v_mov_b32_e32 v24, v9
	v_mov_b32_e32 v23, v55
	v_mov_b32_e32 v22, v7
	v_mov_b32_e32 v21, v163
	v_mov_b32_e32 v20, v5
	v_mov_b32_e32 v19, v161
	v_mov_b32_e32 v18, v3
	v_mov_b32_e32 v17, v49
	v_mov_b32_e32 v16, v1
	v_mov_b32_e32 v15, v62
	v_mov_b32_e32 v13, v60
	v_mov_b32_e32 v11, v58
	v_mov_b32_e32 v9, v56
	v_mov_b32_e32 v7, v54
	v_mov_b32_e32 v5, v162
	v_mov_b32_e32 v3, v160
	v_mov_b32_e32 v1, v48
	s_branch .LBB0_634

.LBB0_651:
	v_exp_f32_e32 v8, v96
	v_exp_f32_e32 v6, v97
	v_exp_f32_e32 v10, v98
	v_exp_f32_e32 v12, v99
	v_exp_f32_e32 v14, v100
	v_exp_f32_e32 v48, v101
	v_exp_f32_e32 v50, v102
	v_exp_f32_e32 v52, v103
	v_cvt_pk_bf16_f32 v2, v8, v6
	v_cvt_pk_bf16_f32 v3, v10, v12
	v_cvt_pk_bf16_f32 v4, v14, v48
	v_cvt_pk_bf16_f32 v5, v50, v52
	v_exp_f32_e32 v54, v106
	v_exp_f32_e32 v56, v107
	v_mfma_f32_32x32x16_bf16 v[112:127], v[44:47], v[2:5], v[112:127]
	v_exp_f32_e32 v44, v104
	v_exp_f32_e32 v46, v105
	v_exp_f32_e32 v58, v108
	v_exp_f32_e32 v60, v109
	v_exp_f32_e32 v9, v0
	v_cvt_pk_bf16_f32 v0, v44, v46
	v_cvt_pk_bf16_f32 v1, v54, v56
	v_mfma_f32_32x32x16_bf16 v[80:95], v[40:43], v[2:5], v[80:95]
	v_exp_f32_e32 v40, v110
	v_exp_f32_e32 v42, v111
	v_cvt_pk_bf16_f32 v2, v58, v60
	v_mov_b32_e32 v7, v9
	v_mov_b32_e32 v11, v9
	v_cvt_pk_bf16_f32 v3, v40, v42
	v_mov_b32_e32 v13, v9
	v_cvt_pk_bf16_f32 v4, v9, v9
	v_mfma_f32_32x32x16_bf16 v[112:127], v[36:39], v[0:3], v[112:127]
	v_add_f32_e64 v36, v8, 0
	v_add_f32_e64 v37, v9, 0
	v_mov_b32_e32 v5, v4
	v_add_f32_e64 v6, v6, v36
	v_add_f32_e64 v7, v7, v37
	v_mov_b32_e32 v15, v9
	v_add_f32_e32 v6, v10, v6
	v_add_f32_e32 v7, v11, v7
	v_mov_b32_e32 v49, v9
	v_add_f32_e32 v10, v12, v6
	v_add_f32_e32 v11, v13, v7
	v_mfma_f32_32x32x16_bf16 v[80:95], v[32:35], v[0:3], v[80:95]
	v_mov_b32_e32 v6, v4
	v_mov_b32_e32 v7, v4
	v_add_f32_e64 v0, v14, v10
	v_add_f32_e64 v1, v15, v11
	v_mov_b32_e32 v51, v9
	v_add_f32_e32 v0, v48, v0
	v_add_f32_e32 v1, v49, v1
	v_mov_b32_e32 v53, v9
	v_add_f32_e32 v0, v50, v0
	v_add_f32_e32 v1, v51, v1
	v_mfma_f32_32x32x16_bf16 v[112:127], v[28:31], v[4:7], v[112:127]
	v_mov_b32_e32 v45, v9
	v_add_f32_e64 v0, v52, v0
	v_add_f32_e64 v1, v53, v1
	v_mov_b32_e32 v47, v9
	v_add_f32_e64 v0, v44, v0
	v_add_f32_e64 v1, v45, v1
	v_mov_b32_e32 v55, v9
	v_add_f32_e32 v0, v46, v0
	v_add_f32_e32 v1, v47, v1
	v_mov_b32_e32 v57, v9
	v_mfma_f32_32x32x16_bf16 v[80:95], v[24:27], v[4:7], v[80:95]
	v_add_f32_e64 v0, v54, v0
	v_add_f32_e64 v1, v55, v1
	v_mov_b32_e32 v59, v9
	v_add_f32_e64 v0, v56, v0
	v_add_f32_e64 v1, v57, v1
	v_mov_b32_e32 v61, v9
	v_add_f32_e32 v0, v58, v0
	v_add_f32_e32 v1, v59, v1
	v_mov_b32_e32 v41, v9
	v_add_f32_e32 v0, v60, v0
	v_add_f32_e32 v1, v61, v1
	v_mfma_f32_32x32x16_bf16 v[112:127], v[20:23], v[4:7], v[112:127]
	v_mov_b32_e32 v43, v9
	v_add_f32_e64 v0, v40, v0
	v_add_f32_e64 v1, v41, v1
	v_add_f32_e64 v0, v42, v0
	v_add_f32_e64 v1, v43, v1
	v_add_f32_e32 v0, v0, v1
	v_add_f32_e32 v202, v202, v0
	v_mfma_f32_32x32x16_bf16 v[80:95], v[16:19], v[4:7], v[80:95]

.LBB0_1367:
	v_exp_f32_e32 v64, v48
	v_exp_f32_e32 v66, v49
	v_exp_f32_e32 v68, v50
	v_exp_f32_e32 v70, v51
	v_exp_f32_e32 v52, v52
	v_exp_f32_e32 v72, v53
	v_exp_f32_e32 v54, v54
	v_exp_f32_e32 v74, v55
	v_cvt_pk_bf16_f32 v48, v64, v66
	v_cvt_pk_bf16_f32 v49, v68, v70
	v_cvt_pk_bf16_f32 v50, v52, v72
	v_cvt_pk_bf16_f32 v51, v54, v74
	v_exp_f32_e32 v56, v56
	v_exp_f32_e32 v76, v57
	s_waitcnt lgkmcnt(0)
	v_mfma_f32_32x32x16_bf16 v[32:47], v[112:115], v[48:51], v[32:47]
	v_exp_f32_e32 v58, v58
	v_exp_f32_e32 v78, v59
	v_exp_f32_e32 v60, v60
	v_exp_f32_e32 v80, v61
	v_exp_f32_e32 v62, v62
	v_exp_f32_e32 v82, v63
	v_exp_f32_e32 v65, v0
	v_mfma_f32_32x32x16_bf16 v[16:31], v[108:111], v[48:51], v[16:31]
	v_exp_f32_e32 v67, v1
	v_exp_f32_e32 v69, v2
	v_exp_f32_e32 v71, v3
	v_cvt_pk_bf16_f32 v0, v56, v76
	v_cvt_pk_bf16_f32 v1, v58, v78
	v_cvt_pk_bf16_f32 v2, v60, v80
	v_cvt_pk_bf16_f32 v3, v62, v82
	v_exp_f32_e32 v53, v4
	v_exp_f32_e32 v73, v5
	v_mfma_f32_32x32x16_bf16 v[32:47], v[104:107], v[0:3], v[32:47]
	v_exp_f32_e32 v55, v6
	v_exp_f32_e32 v75, v7
	v_add_f32_e64 v4, v64, 0
	v_add_f32_e64 v5, v65, 0
	v_exp_f32_e32 v57, v8
	v_add_f32_e32 v4, v66, v4
	v_add_f32_e32 v5, v67, v5
	v_exp_f32_e32 v77, v9
	v_add_f32_e32 v4, v68, v4
	v_add_f32_e32 v5, v69, v5
	v_mfma_f32_32x32x16_bf16 v[16:31], v[100:103], v[0:3], v[16:31]
	v_cvt_pk_bf16_f32 v0, v65, v67
	v_cvt_pk_bf16_f32 v1, v69, v71
	v_cvt_pk_bf16_f32 v2, v53, v73
	v_cvt_pk_bf16_f32 v3, v55, v75
	v_add_f32_e64 v8, v70, v4
	v_add_f32_e64 v9, v71, v5
	v_exp_f32_e32 v59, v10
	v_exp_f32_e32 v79, v11
	v_mfma_f32_32x32x16_bf16 v[32:47], v[96:99], v[0:3], v[32:47]
	v_exp_f32_e32 v61, v12
	v_exp_f32_e32 v81, v13
	v_exp_f32_e32 v63, v14
	v_exp_f32_e32 v83, v15
	v_cvt_pk_bf16_f32 v4, v57, v77
	v_cvt_pk_bf16_f32 v5, v59, v79
	v_cvt_pk_bf16_f32 v6, v61, v81
	v_mfma_f32_32x32x16_bf16 v[16:31], v[92:95], v[0:3], v[16:31]
	v_add_f32_e64 v0, v52, v8
	v_add_f32_e64 v1, v53, v9
	v_cvt_pk_bf16_f32 v7, v63, v83
	v_add_f32_e64 v0, v72, v0
	v_add_f32_e64 v1, v73, v1
	v_add_f32_e32 v0, v54, v0
	v_add_f32_e32 v1, v55, v1
	s_nop 0
	v_add_f32_e32 v0, v74, v0
	v_add_f32_e32 v1, v75, v1
	v_mfma_f32_32x32x16_bf16 v[32:47], v[88:91], v[4:7], v[32:47]
	v_add_f32_e64 v0, v56, v0
	v_add_f32_e64 v1, v57, v1
	v_add_f32_e64 v0, v76, v0
	v_add_f32_e64 v1, v77, v1
	v_add_f32_e64 v0, v58, v0
	v_add_f32_e64 v1, v59, v1
	v_add_f32_e32 v0, v78, v0
	v_add_f32_e32 v1, v79, v1
	v_mfma_f32_32x32x16_bf16 v[16:31], v[84:87], v[4:7], v[16:31]
	v_add_f32_e64 v0, v60, v0
	v_add_f32_e64 v1, v61, v1
	v_add_f32_e64 v0, v80, v0
	v_add_f32_e64 v1, v81, v1
	v_add_f32_e64 v0, v62, v0
	v_add_f32_e64 v1, v63, v1
	v_add_f32_e32 v0, v82, v0
	v_add_f32_e32 v1, v83, v1
	s_nop 0
	v_add_f32_e32 v0, v0, v1
	v_add_f32_e32 v164, v164, v0

.LBB0_1397:
	v_exp_f32_e32 v174, v64
	v_exp_f32_e32 v176, v65
	v_exp_f32_e32 v182, v66
	v_exp_f32_e32 v184, v67
	v_exp_f32_e32 v68, v68
	v_exp_f32_e32 v186, v69
	v_exp_f32_e32 v70, v70
	v_exp_f32_e32 v188, v71
	v_cvt_pk_bf16_f32 v64, v174, v176
	v_cvt_pk_bf16_f32 v65, v182, v184
	v_cvt_pk_bf16_f32 v66, v68, v186
	v_cvt_pk_bf16_f32 v67, v70, v188
	v_exp_f32_e32 v72, v72
	v_exp_f32_e32 v190, v73
	v_mfma_f32_32x32x16_bf16 v[32:47], v[140:143], v[64:67], v[32:47]
	v_exp_f32_e32 v74, v74
	v_exp_f32_e32 v192, v75
	v_exp_f32_e32 v76, v76
	v_exp_f32_e32 v140, v77
	v_exp_f32_e32 v78, v78
	v_exp_f32_e32 v142, v79
	v_exp_f32_e32 v175, v48
	v_mfma_f32_32x32x16_bf16 v[16:31], v[136:139], v[64:67], v[16:31]
	v_exp_f32_e32 v177, v49
	v_exp_f32_e32 v183, v50
	v_exp_f32_e32 v185, v51
	v_cvt_pk_bf16_f32 v48, v72, v190
	v_cvt_pk_bf16_f32 v49, v74, v192
	v_cvt_pk_bf16_f32 v50, v76, v140
	v_cvt_pk_bf16_f32 v51, v78, v142
	v_exp_f32_e32 v69, v52
	v_exp_f32_e32 v187, v53
	v_mfma_f32_32x32x16_bf16 v[32:47], v[132:135], v[48:51], v[32:47]
	v_exp_f32_e32 v71, v54
	v_exp_f32_e32 v189, v55
	v_add_f32_e64 v52, v174, 0
	v_add_f32_e64 v53, v175, 0
	v_exp_f32_e32 v73, v56
	v_add_f32_e32 v52, v176, v52
	v_add_f32_e32 v53, v177, v53
	v_exp_f32_e32 v191, v57
	v_add_f32_e32 v52, v182, v52
	v_add_f32_e32 v53, v183, v53
	v_mfma_f32_32x32x16_bf16 v[16:31], v[128:131], v[48:51], v[16:31]
	v_cvt_pk_bf16_f32 v48, v175, v177
	v_cvt_pk_bf16_f32 v49, v183, v185
	v_cvt_pk_bf16_f32 v50, v69, v187
	v_cvt_pk_bf16_f32 v51, v71, v189
	v_add_f32_e64 v56, v184, v52
	v_add_f32_e64 v57, v185, v53
	v_exp_f32_e32 v75, v58
	v_exp_f32_e32 v193, v59
	v_mfma_f32_32x32x16_bf16 v[32:47], v[124:127], v[48:51], v[32:47]
	v_exp_f32_e32 v77, v60
	v_exp_f32_e32 v141, v61
	v_exp_f32_e32 v79, v62
	v_exp_f32_e32 v143, v63
	v_cvt_pk_bf16_f32 v52, v73, v191
	v_cvt_pk_bf16_f32 v53, v75, v193
	v_cvt_pk_bf16_f32 v54, v77, v141
	v_mfma_f32_32x32x16_bf16 v[16:31], v[120:123], v[48:51], v[16:31]
	v_add_f32_e64 v48, v68, v56
	v_add_f32_e64 v49, v69, v57
	v_cvt_pk_bf16_f32 v55, v79, v143
	v_add_f32_e64 v48, v186, v48
	v_add_f32_e64 v49, v187, v49
	s_mov_b64 s[4:5], 0
	v_add_f32_e32 v48, v70, v48
	v_add_f32_e32 v49, v71, v49
	s_nop 0
	v_add_f32_e32 v48, v188, v48
	v_add_f32_e32 v49, v189, v49
	v_mfma_f32_32x32x16_bf16 v[32:47], v[116:119], v[52:55], v[32:47]
	v_add_f32_e64 v48, v72, v48
	v_add_f32_e64 v49, v73, v49
	v_add_f32_e64 v48, v190, v48
	v_add_f32_e64 v49, v191, v49
	v_add_f32_e64 v48, v74, v48
	v_add_f32_e64 v49, v75, v49
	v_add_f32_e32 v48, v192, v48
	v_add_f32_e32 v49, v193, v49
	v_mfma_f32_32x32x16_bf16 v[16:31], v[112:115], v[52:55], v[16:31]
	v_add_f32_e64 v48, v76, v48
	v_add_f32_e64 v49, v77, v49
	v_add_f32_e64 v48, v140, v48
	v_add_f32_e64 v49, v141, v49
	v_add_f32_e64 v48, v78, v48
	v_add_f32_e64 v49, v79, v49
	v_add_f32_e32 v48, v142, v48
	v_add_f32_e32 v49, v143, v49
	s_nop 0
	v_add_f32_e32 v48, v48, v49
	v_add_f32_e32 v164, v164, v48

.LBB0_1411:
	v_exp_f32_e32 v64, v48
	v_exp_f32_e32 v66, v49
	v_exp_f32_e32 v68, v50
	v_exp_f32_e32 v70, v51
	v_exp_f32_e32 v52, v52
	v_exp_f32_e32 v72, v53
	v_exp_f32_e32 v54, v54
	v_exp_f32_e32 v74, v55
	v_cvt_pk_bf16_f32 v48, v64, v66
	v_cvt_pk_bf16_f32 v49, v68, v70
	v_cvt_pk_bf16_f32 v50, v52, v72
	v_cvt_pk_bf16_f32 v51, v54, v74
	v_exp_f32_e32 v56, v56
	v_exp_f32_e32 v76, v57
	v_mfma_f32_32x32x16_bf16 v[32:47], v[112:115], v[48:51], v[32:47]
	v_exp_f32_e32 v58, v58
	v_exp_f32_e32 v78, v59
	v_exp_f32_e32 v60, v60
	v_exp_f32_e32 v80, v61
	v_exp_f32_e32 v62, v62
	v_exp_f32_e32 v82, v63
	v_exp_f32_e32 v65, v0
	v_mfma_f32_32x32x16_bf16 v[16:31], v[108:111], v[48:51], v[16:31]
	v_exp_f32_e32 v67, v1
	v_exp_f32_e32 v69, v2
	v_exp_f32_e32 v71, v3
	v_cvt_pk_bf16_f32 v0, v56, v76
	v_cvt_pk_bf16_f32 v1, v58, v78
	v_cvt_pk_bf16_f32 v2, v60, v80
	v_cvt_pk_bf16_f32 v3, v62, v82
	v_exp_f32_e32 v53, v4
	v_exp_f32_e32 v73, v5
	v_mfma_f32_32x32x16_bf16 v[32:47], v[104:107], v[0:3], v[32:47]
	v_exp_f32_e32 v55, v6
	v_exp_f32_e32 v75, v7
	v_add_f32_e64 v4, v64, 0
	v_add_f32_e64 v5, v65, 0
	v_exp_f32_e32 v57, v8
	v_add_f32_e32 v4, v66, v4
	v_add_f32_e32 v5, v67, v5
	v_exp_f32_e32 v77, v9
	v_add_f32_e32 v4, v68, v4
	v_add_f32_e32 v5, v69, v5
	v_mfma_f32_32x32x16_bf16 v[16:31], v[100:103], v[0:3], v[16:31]
	v_cvt_pk_bf16_f32 v0, v65, v67
	v_cvt_pk_bf16_f32 v1, v69, v71
	v_cvt_pk_bf16_f32 v2, v53, v73
	v_cvt_pk_bf16_f32 v3, v55, v75
	v_add_f32_e64 v8, v70, v4
	v_add_f32_e64 v9, v71, v5
	v_exp_f32_e32 v59, v10
	v_exp_f32_e32 v79, v11
	v_mfma_f32_32x32x16_bf16 v[32:47], v[96:99], v[0:3], v[32:47]
	v_exp_f32_e32 v61, v12
	v_exp_f32_e32 v81, v13
	v_exp_f32_e32 v63, v14
	v_exp_f32_e32 v83, v15
	v_cvt_pk_bf16_f32 v4, v57, v77
	v_cvt_pk_bf16_f32 v5, v59, v79
	v_cvt_pk_bf16_f32 v6, v61, v81
	v_mfma_f32_32x32x16_bf16 v[16:31], v[92:95], v[0:3], v[16:31]
	v_add_f32_e64 v0, v52, v8
	v_add_f32_e64 v1, v53, v9
	v_cvt_pk_bf16_f32 v7, v63, v83
	v_add_f32_e64 v0, v72, v0
	v_add_f32_e64 v1, v73, v1
	v_add_f32_e32 v0, v54, v0
	v_add_f32_e32 v1, v55, v1
	s_nop 0
	v_add_f32_e32 v0, v74, v0
	v_add_f32_e32 v1, v75, v1
	v_mfma_f32_32x32x16_bf16 v[32:47], v[88:91], v[4:7], v[32:47]
	v_add_f32_e64 v0, v56, v0
	v_add_f32_e64 v1, v57, v1
	v_add_f32_e64 v0, v76, v0
	v_add_f32_e64 v1, v77, v1
	v_add_f32_e64 v0, v58, v0
	v_add_f32_e64 v1, v59, v1
	v_add_f32_e32 v0, v78, v0
	v_add_f32_e32 v1, v79, v1
	v_mfma_f32_32x32x16_bf16 v[16:31], v[84:87], v[4:7], v[16:31]
	v_add_f32_e64 v0, v60, v0
	v_add_f32_e64 v1, v61, v1
	v_add_f32_e64 v0, v80, v0
	v_add_f32_e64 v1, v81, v1
	v_add_f32_e64 v0, v62, v0
	v_add_f32_e64 v1, v63, v1
	v_add_f32_e32 v0, v82, v0
	v_add_f32_e32 v1, v83, v1
	s_nop 0
	v_add_f32_e32 v0, v0, v1
	v_add_f32_e32 v164, v164, v0

.LBB0_1440:
	v_exp_f32_e32 v194, v80
	v_exp_f32_e32 v196, v81
	v_exp_f32_e32 v198, v82
	v_exp_f32_e32 v200, v83
	v_exp_f32_e32 v84, v84
	v_exp_f32_e32 v202, v85
	v_exp_f32_e32 v86, v86
	v_exp_f32_e32 v204, v87
	v_cvt_pk_bf16_f32 v80, v194, v196
	v_cvt_pk_bf16_f32 v81, v198, v200
	v_cvt_pk_bf16_f32 v82, v84, v202
	v_cvt_pk_bf16_f32 v83, v86, v204
	v_exp_f32_e32 v88, v88
	v_exp_f32_e32 v206, v89
	v_mfma_f32_32x32x16_bf16 v[48:63], v[156:159], v[80:83], v[48:63]
	v_exp_f32_e32 v90, v90
	v_exp_f32_e32 v208, v91
	v_exp_f32_e32 v92, v92
	v_exp_f32_e32 v156, v93
	v_exp_f32_e32 v94, v94
	v_exp_f32_e32 v158, v95
	v_exp_f32_e32 v195, v64
	v_mfma_f32_32x32x16_bf16 v[32:47], v[152:155], v[80:83], v[32:47]
	v_exp_f32_e32 v197, v65
	v_exp_f32_e32 v199, v66
	v_exp_f32_e32 v201, v67
	v_cvt_pk_bf16_f32 v64, v88, v206
	v_cvt_pk_bf16_f32 v65, v90, v208
	v_cvt_pk_bf16_f32 v66, v92, v156
	v_cvt_pk_bf16_f32 v67, v94, v158
	v_exp_f32_e32 v85, v68
	v_exp_f32_e32 v203, v69
	v_mfma_f32_32x32x16_bf16 v[48:63], v[148:151], v[64:67], v[48:63]
	v_exp_f32_e32 v87, v70
	v_exp_f32_e32 v205, v71
	v_add_f32_e64 v68, v194, 0
	v_add_f32_e64 v69, v195, 0
	v_exp_f32_e32 v89, v72
	v_add_f32_e32 v68, v196, v68
	v_add_f32_e32 v69, v197, v69
	v_exp_f32_e32 v207, v73
	v_add_f32_e32 v68, v198, v68
	v_add_f32_e32 v69, v199, v69
	v_mfma_f32_32x32x16_bf16 v[32:47], v[144:147], v[64:67], v[32:47]
	v_cvt_pk_bf16_f32 v64, v195, v197
	v_cvt_pk_bf16_f32 v65, v199, v201
	v_cvt_pk_bf16_f32 v66, v85, v203
	v_cvt_pk_bf16_f32 v67, v87, v205
	v_add_f32_e64 v72, v200, v68
	v_add_f32_e64 v73, v201, v69
	v_exp_f32_e32 v91, v74
	v_exp_f32_e32 v209, v75
	v_mfma_f32_32x32x16_bf16 v[48:63], v[140:143], v[64:67], v[48:63]
	v_exp_f32_e32 v93, v76
	v_exp_f32_e32 v157, v77
	v_exp_f32_e32 v95, v78
	v_exp_f32_e32 v159, v79
	v_cvt_pk_bf16_f32 v68, v89, v207
	v_cvt_pk_bf16_f32 v69, v91, v209
	v_cvt_pk_bf16_f32 v70, v93, v157
	v_mfma_f32_32x32x16_bf16 v[32:47], v[136:139], v[64:67], v[32:47]
	v_add_f32_e64 v64, v84, v72
	v_add_f32_e64 v65, v85, v73
	v_cvt_pk_bf16_f32 v71, v95, v159
	v_add_f32_e64 v64, v202, v64
	v_add_f32_e64 v65, v203, v65
	s_mov_b64 s[4:5], 0
	v_add_f32_e32 v64, v86, v64
	v_add_f32_e32 v65, v87, v65
	s_nop 0
	v_add_f32_e32 v64, v204, v64
	v_add_f32_e32 v65, v205, v65
	v_mfma_f32_32x32x16_bf16 v[48:63], v[132:135], v[68:71], v[48:63]
	v_add_f32_e64 v64, v88, v64
	v_add_f32_e64 v65, v89, v65
	v_add_f32_e64 v64, v206, v64
	v_add_f32_e64 v65, v207, v65
	v_add_f32_e64 v64, v90, v64
	v_add_f32_e64 v65, v91, v65
	v_add_f32_e32 v64, v208, v64
	v_add_f32_e32 v65, v209, v65
	v_mfma_f32_32x32x16_bf16 v[32:47], v[128:131], v[68:71], v[32:47]
	v_add_f32_e64 v64, v92, v64
	v_add_f32_e64 v65, v93, v65
	v_add_f32_e64 v64, v156, v64
	v_add_f32_e64 v65, v157, v65
	v_add_f32_e64 v64, v94, v64
	v_add_f32_e64 v65, v95, v65
	v_add_f32_e32 v64, v158, v64
	v_add_f32_e32 v65, v159, v65
	s_nop 0
	v_add_f32_e32 v64, v64, v65
	v_add_f32_e32 v184, v184, v64

.LBB0_1454:
	v_exp_f32_e32 v66, v16
	v_exp_f32_e32 v68, v17
	v_exp_f32_e32 v70, v18
	v_exp_f32_e32 v72, v19
	v_exp_f32_e32 v74, v20
	v_exp_f32_e32 v76, v21
	v_exp_f32_e32 v78, v22
	v_exp_f32_e32 v96, v23
	v_cvt_pk_bf16_f32 v16, v66, v68
	v_cvt_pk_bf16_f32 v17, v70, v72
	v_cvt_pk_bf16_f32 v18, v74, v76
	v_cvt_pk_bf16_f32 v19, v78, v96
	v_exp_f32_e32 v24, v24
	v_exp_f32_e32 v98, v25
	v_mfma_f32_32x32x16_bf16 v[48:63], v[112:115], v[16:19], v[48:63]
	v_exp_f32_e32 v26, v26
	v_exp_f32_e32 v112, v27
	v_exp_f32_e32 v28, v28
	v_exp_f32_e32 v114, v29
	v_exp_f32_e32 v67, v64
	v_exp_f32_e32 v30, v30
	v_exp_f32_e32 v64, v31
	v_mfma_f32_32x32x16_bf16 v[32:47], v[108:111], v[16:19], v[32:47]
	v_cvt_pk_bf16_f32 v16, v24, v98
	v_cvt_pk_bf16_f32 v17, v26, v112
	v_cvt_pk_bf16_f32 v18, v28, v114
	v_cvt_pk_bf16_f32 v19, v30, v64
	v_mov_b32_e32 v69, v67
	v_add_f32_e64 v22, v66, 0
	v_add_f32_e64 v23, v67, 0
	v_mov_b32_e32 v71, v67
	v_mfma_f32_32x32x16_bf16 v[48:63], v[104:107], v[16:19], v[48:63]
	v_add_f32_e64 v22, v68, v22
	v_add_f32_e64 v23, v69, v23
	v_mov_b32_e32 v73, v67
	v_cvt_pk_bf16_f32 v20, v67, v67
	v_add_f32_e64 v22, v70, v22
	v_add_f32_e64 v23, v71, v23
	v_mov_b32_e32 v21, v20
	v_add_f32_e32 v68, v72, v22
	v_add_f32_e32 v69, v73, v23
	v_mov_b32_e32 v22, v20
	v_mfma_f32_32x32x16_bf16 v[32:47], v[100:103], v[16:19], v[32:47]
	v_mov_b32_e32 v23, v20
	v_mov_b32_e32 v75, v67
	v_mov_b32_e32 v77, v67
	v_add_f32_e64 v16, v74, v68
	v_add_f32_e64 v17, v75, v69
	v_mov_b32_e32 v79, v67
	v_add_f32_e32 v16, v76, v16
	v_add_f32_e32 v17, v77, v17
	v_mov_b32_e32 v97, v67
	v_mfma_f32_32x32x16_bf16 v[48:63], v[92:95], v[20:23], v[48:63]
	v_add_f32_e64 v16, v78, v16
	v_add_f32_e64 v17, v79, v17
	v_mov_b32_e32 v25, v67
	v_add_f32_e64 v16, v96, v16
	v_add_f32_e64 v17, v97, v17
	v_mov_b32_e32 v99, v67
	v_add_f32_e32 v16, v24, v16
	v_add_f32_e32 v17, v25, v17
	v_mov_b32_e32 v27, v67
	v_add_f32_e32 v16, v98, v16
	v_add_f32_e32 v17, v99, v17
	v_mfma_f32_32x32x16_bf16 v[32:47], v[88:91], v[20:23], v[32:47]
	v_mov_b32_e32 v113, v67
	v_add_f32_e64 v16, v26, v16
	v_add_f32_e64 v17, v27, v17
	v_mov_b32_e32 v29, v67
	v_add_f32_e64 v16, v112, v16
	v_add_f32_e64 v17, v113, v17
	v_mov_b32_e32 v115, v67
	v_add_f32_e32 v16, v28, v16
	v_add_f32_e32 v17, v29, v17
	v_mov_b32_e32 v31, v67
	v_mfma_f32_32x32x16_bf16 v[48:63], v[84:87], v[20:23], v[48:63]
	v_add_f32_e64 v16, v114, v16
	v_add_f32_e64 v17, v115, v17
	v_mov_b32_e32 v65, v67
	v_add_f32_e64 v16, v30, v16
	v_add_f32_e64 v17, v31, v17
	v_add_f32_e32 v16, v64, v16
	v_add_f32_e32 v17, v65, v17
	s_nop 0
	v_add_f32_e32 v16, v16, v17
	v_mfma_f32_32x32x16_bf16 v[32:47], v[80:83], v[20:23], v[32:47]
	v_add_f32_e32 v184, v184, v16
